# nt on x loads, out stores, PG loads; P0 transpose loop waits only for loads
# baseline (speedup 1.0000x reference)
; #define LAS __attribute__((address_space(3)))
; __device__ __forceinline__ void p0_prologue(const Ptrs& P, LAS unsigned char* lds, int vcu, int G, int tid) {
;     ...
;     if (gw < NITEMS) {
;         TItem cur = t_decode(P, gw, lane); f32x4 v[8]; t_load(cur, v);
;         for (int it = gw; it < NITEMS; it += NGW) {
;             const int nit = it + NGW; const bool has_n = nit < NITEMS;
;             f32x4 nv[8];
;             const TItem nxt = t_decode(P, has_n ? nit : it, lane); t_load(nxt, nv);
;             const int c4 = 4 * (lane & 7), r8 = lane >> 3;
; #pragma unroll
;             for (int j = 0; j < 8; ++j) { LAS float* d = scr + (8 * j + r8) * 33 + c4; d[0] = v[j][0]; d[1] = v[j][1]; d[2] = v[j][2]; d[3] = v[j][3]; }
.LBB0_36:
	s_lshl_b32 s20, s39, 14
	s_mov_b32 s21, 0
	s_add_i32 s24, s20, 0
	s_mul_i32 s20, s22, 0xe0
	v_lshl_add_u64 v[10:11], v[34:35], 0, s[20:21]
	s_lshl_b32 s20, s22, 5
	s_sub_u32 s22, 0, s20
	s_subb_u32 s23, 0, 0
	v_lshl_add_u64 v[12:13], v[10:11], 0, s[22:23]
	v_lshl_add_u64 v[18:19], v[12:13], 0, s[22:23]
	v_lshl_add_u64 v[20:21], v[18:19], 0, s[22:23]
	v_lshl_add_u64 v[26:27], v[20:21], 0, s[22:23]
	v_lshl_add_u64 v[28:29], v[26:27], 0, s[22:23]
	v_lshl_add_u64 v[38:39], v[28:29], 0, s[22:23]
	global_load_dwordx4 v[2:5], v[10:11], off nt
	global_load_dwordx4 v[6:9], v[12:13], off nt
	s_nop 0
	global_load_dwordx4 v[10:13], v[18:19], off nt
	global_load_dwordx4 v[14:17], v[20:21], off nt
	s_nop 0
	global_load_dwordx4 v[18:21], v[26:27], off nt
	global_load_dwordx4 v[22:25], v[28:29], off nt
	s_nop 0
	global_load_dwordx4 v[26:29], v[38:39], off nt
	global_load_dwordx4 v[30:33], v[34:35], off nt
	v_lshlrev_b32_e32 v34, 3, v80
	v_and_or_b32 v82, v34, 24, v37
	v_and_b32_e32 v34, 7, v36
	v_lshl_add_u32 v35, v34, 4, s24
	v_lshlrev_b32_e32 v66, 3, v34
	v_mul_u32_u24_e32 v34, 0x420, v34
	v_mov_b32_e32 v69, 0
	v_mul_u32_u24_e32 v36, 0x84, v81
	v_lshlrev_b32_e32 v37, 2, v81
	v_lshlrev_b32_e32 v70, 12, v81
	v_mov_b32_e32 v67, v69
	v_or_b32_e32 v83, 0x2000, v82
	v_add3_u32 v84, s24, v34, v37
	v_mov_b32_e32 v71, v69
	v_or_b32_e32 v72, 0x8000, v70
	v_mov_b32_e32 v73, v69
	v_or_b32_e32 v74, 0x10000, v70
	v_mov_b32_e32 v75, v69
	s_mov_b32 s48, 0x18000
	v_or_b32_e32 v76, 0x18000, v70
	v_mov_b32_e32 v77, v69
	s_movk_i32 s49, 0x800
	v_add_u32_e32 v85, v35, v36
	s_mov_b32 s50, s3
	s_waitcnt vmcnt(0)
	s_branch .LBB0_39

; __device__ __forceinline__ void p0_prologue(const Ptrs& P, LAS unsigned char* lds, int vcu, int G, int tid) {
;     ...
;             asm volatile("s_waitcnt lgkmcnt(0)" ::: "memory");
; #pragma unroll
;             for (int j = 0; j < 8; ++j) v[j] = nv[j];
;             cur = nxt;
;         }
.LBB0_38:
	s_waitcnt lgkmcnt(0)
	s_waitcnt vmcnt(4)
	v_mov_b64_e32 v[30:31], v[62:63]
	v_mov_b64_e32 v[26:27], v[34:35]
	v_mov_b64_e32 v[22:23], v[38:39]
	v_mov_b64_e32 v[18:19], v[42:43]
	v_mov_b64_e32 v[14:15], v[46:47]
	v_mov_b64_e32 v[10:11], v[50:51]
	v_mov_b64_e32 v[6:7], v[54:55]
	s_waitcnt lgkmcnt(0)
	v_mov_b64_e32 v[2:3], v[58:59]
	s_andn2_b64 vcc, exec, s[22:23]
	v_mov_b64_e32 v[32:33], v[64:65]
	v_mov_b64_e32 v[28:29], v[36:37]
	v_mov_b64_e32 v[24:25], v[40:41]
	v_mov_b64_e32 v[20:21], v[44:45]
	v_mov_b64_e32 v[16:17], v[48:49]
	v_mov_b64_e32 v[12:13], v[52:53]
	v_mov_b64_e32 v[8:9], v[56:57]
	v_mov_b64_e32 v[4:5], v[60:61]
	s_mov_b32 s51, s52
	s_mov_b64 s[18:19], s[24:25]
	s_cbranch_vccz .LBB0_65

; #define LAS __attribute__((address_space(3)))
; __device__ __forceinline__ void p0_prologue(const Ptrs& P, LAS unsigned char* lds, int vcu, int G, int tid) {
;     ...
;         for (int it = gw; it < NITEMS; it += NGW) {
;             const int nit = it + NGW; const bool has_n = nit < NITEMS;
;             f32x4 nv[8];
;             const TItem nxt = t_decode(P, has_n ? nit : it, lane); t_load(nxt, nv);
;             const int c4 = 4 * (lane & 7), r8 = lane >> 3;
; #pragma unroll
;             for (int j = 0; j < 8; ++j) { LAS float* d = scr + (8 * j + r8) * 33 + c4; d[0] = v[j][0]; d[1] = v[j][1]; d[2] = v[j][2]; d[3] = v[j][3]; }
;             asm volatile("s_waitcnt lgkmcnt(0)" ::: "memory");
;             const int c = lane & 7;
;             if (cur.f8) {
; #pragma unroll
;                 for (int j = 0; j < 4; ++j) { const int n = (lane >> 3) + 8 * j; const LAS float* sp = scr + (8 * c) * 33 + n;
;                     int w0 = 0, w1 = 0;
;                     w0 = __builtin_amdgcn_cvt_pk_fp8_f32(sp[0 * 33] * F8_SW, sp[1 * 33] * F8_SW, w0, false); w0 = __builtin_amdgcn_cvt_pk_fp8_f32(sp[2 * 33] * F8_SW, sp[3 * 33] * F8_SW, w0, true);
;                     w1 = __builtin_amdgcn_cvt_pk_fp8_f32(sp[4 * 33] * F8_SW, sp[5 * 33] * F8_SW, w1, false); w1 = __builtin_amdgcn_cvt_pk_fp8_f32(sp[6 * 33] * F8_SW, sp[7 * 33] * F8_SW, w1, true);
;                     u32x2 o; o.x = (unsigned)w0; o.y = (unsigned)w1;
;                     *(u32x2*)((unsigned char*)cur.dst + (size_t)n * cur.ldk + 8 * c) = o; }
.LBB0_62:
	s_lshl_b32 s20, s26, 5
	v_lshl_add_u64 v[42:43], v[78:79], 0, s[20:21]
	v_lshl_add_u64 v[44:45], v[42:43], 0, s[20:21]
	v_lshl_add_u64 v[50:51], v[44:45], 0, s[20:21]
	v_lshl_add_u64 v[52:53], v[50:51], 0, s[20:21]
	v_lshl_add_u64 v[58:59], v[52:53], 0, s[20:21]
	v_lshl_add_u64 v[60:61], v[58:59], 0, s[20:21]
	global_load_dwordx4 v[34:37], v[42:43], off nt
	global_load_dwordx4 v[38:41], v[44:45], off nt
	s_nop 0
	global_load_dwordx4 v[42:45], v[50:51], off nt
	global_load_dwordx4 v[46:49], v[52:53], off nt
	s_nop 0
	global_load_dwordx4 v[50:53], v[58:59], off nt
	global_load_dwordx4 v[54:57], v[60:61], off nt
	v_lshl_add_u64 v[86:87], v[60:61], 0, s[20:21]
	global_load_dwordx4 v[62:65], v[78:79], off nt
	global_load_dwordx4 v[58:61], v[86:87], off nt
	s_waitcnt vmcnt(12)
	ds_write2_b32 v85, v30, v31 offset1:1
	ds_write2_b32 v85, v32, v33 offset0:2 offset1:3
	v_add_u32_e32 v30, 0x420, v85
	ds_write2_b32 v30, v26, v27 offset1:1
	v_add_u32_e32 v26, 0x428, v85
	ds_write2_b32 v26, v28, v29 offset1:1
	v_add_u32_e32 v26, 0x840, v85
	ds_write2_b32 v26, v22, v23 offset1:1
	v_add_u32_e32 v22, 0x848, v85
	ds_write2_b32 v22, v24, v25 offset1:1
	v_add_u32_e32 v22, 0xc60, v85
	ds_write2_b32 v22, v18, v19 offset1:1
	v_add_u32_e32 v18, 0xc68, v85
	ds_write2_b32 v18, v20, v21 offset1:1
	v_add_u32_e32 v18, 0x1080, v85
	ds_write2_b32 v18, v14, v15 offset1:1
	v_add_u32_e32 v14, 0x1088, v85
	ds_write2_b32 v14, v16, v17 offset1:1
	v_add_u32_e32 v14, 0x14a0, v85
	ds_write2_b32 v14, v10, v11 offset1:1
	v_add_u32_e32 v10, 0x14a8, v85
	ds_write2_b32 v10, v12, v13 offset1:1
	v_add_u32_e32 v10, 0x18c0, v85
	ds_write2_b32 v10, v6, v7 offset1:1
	v_add_u32_e32 v6, 0x18c8, v85
	ds_write2_b32 v6, v8, v9 offset1:1
	v_add_u32_e32 v6, 0x1ce0, v85
	ds_write2_b32 v6, v2, v3 offset1:1
	v_add_u32_e32 v2, 0x1ce8, v85
	ds_write2_b32 v2, v4, v5 offset1:1
	s_waitcnt lgkmcnt(0)
	ds_read_b32 v2, v84
	s_cmp_eq_u32 s51, 0
	s_cbranch_scc1 .LBB0_64
	ds_read2_b32 v[4:5], v84 offset0:24 offset1:33
	ds_read2_b32 v[10:11], v84 offset0:57 offset1:66
	ds_read2_b32 v[12:13], v84 offset0:90 offset1:99
	s_waitcnt lgkmcnt(3)
	v_mul_f32_e32 v3, 0x43800000, v2
	v_mov_b32_e32 v8, v69
	s_waitcnt lgkmcnt(2)
	v_mul_f32_e32 v5, 0x43800000, v5
	ds_read2_b32 v[14:15], v84 offset0:123 offset1:132
	ds_read2_b32 v[16:17], v84 offset0:156 offset1:165
	v_cvt_pk_fp8_f32 v8, v3, v5
	s_waitcnt lgkmcnt(3)
	v_mul_f32_e32 v3, 0x43800000, v11
	s_waitcnt lgkmcnt(2)
	v_mul_f32_e32 v5, 0x43800000, v13
	ds_read2_b32 v[18:19], v84 offset0:189 offset1:198
	ds_read2_b32 v[20:21], v84 offset0:222 offset1:231
	v_cvt_pk_fp8_f32 v8, v3, v5 op_sel:[0,0,1]
	s_waitcnt lgkmcnt(3)
	v_mul_f32_e32 v3, 0x43800000, v15
	s_waitcnt lgkmcnt(2)
	v_mul_f32_e32 v5, 0x43800000, v17
	v_mov_b32_e32 v9, v69
	ds_read2_b32 v[22:23], v84 offset0:8 offset1:16
	ds_read2_b32 v[24:25], v84 offset0:41 offset1:49
	v_cvt_pk_fp8_f32 v9, v3, v5
	ds_read2_b32 v[28:29], v84 offset0:74 offset1:82
	ds_read2_b32 v[30:31], v84 offset0:107 offset1:115
	ds_read2_b32 v[32:33], v84 offset0:140 offset1:148
	ds_read2_b32 v[78:79], v84 offset0:173 offset1:181
	s_waitcnt lgkmcnt(7)
	v_mul_f32_e32 v3, 0x43800000, v19
	s_waitcnt lgkmcnt(6)
	v_mul_f32_e32 v5, 0x43800000, v21
	v_cvt_pk_fp8_f32 v9, v3, v5 op_sel:[0,0,1]
	s_waitcnt lgkmcnt(5)
	v_mul_f32_e32 v3, 0x43800000, v22
	s_waitcnt lgkmcnt(4)
	v_mul_f32_e32 v5, 0x43800000, v24
	v_mov_b32_e32 v26, v69
	ds_read2_b32 v[86:87], v84 offset0:206 offset1:214
	ds_read2_b32 v[88:89], v84 offset0:239 offset1:247
	v_cvt_pk_fp8_f32 v26, v3, v5
	s_waitcnt lgkmcnt(3)
	v_mul_f32_e32 v11, 0x43800000, v32
	s_waitcnt lgkmcnt(2)
	v_mul_f32_e32 v13, 0x43800000, v78
	v_mov_b32_e32 v27, v69
	v_cvt_pk_fp8_f32 v27, v11, v13
	v_mul_f32_e32 v3, 0x43800000, v28
	v_mul_f32_e32 v5, 0x43800000, v30
	v_cvt_pk_fp8_f32 v26, v3, v5 op_sel:[0,0,1]
	s_waitcnt lgkmcnt(1)
	v_mul_f32_e32 v3, 0x43800000, v86
	s_waitcnt lgkmcnt(0)
	v_mul_f32_e32 v5, 0x43800000, v88
	v_cvt_pk_fp8_f32 v27, v3, v5 op_sel:[0,0,1]
	v_lshl_add_u64 v[6:7], s[18:19], 0, v[66:67]
	v_lshl_add_u64 v[92:93], v[6:7], 0, v[70:71]
	global_store_dwordx2 v[92:93], v[8:9], off
	v_lshl_add_u64 v[8:9], v[6:7], 0, v[72:73]
	global_store_dwordx2 v[8:9], v[26:27], off
	v_mul_f32_e32 v3, 0x43800000, v23
	v_mul_f32_e32 v5, 0x43800000, v25
	v_mov_b32_e32 v8, v69
	v_cvt_pk_fp8_f32 v8, v3, v5
	v_mul_f32_e32 v11, 0x43800000, v33
	v_mul_f32_e32 v13, 0x43800000, v79
	v_mov_b32_e32 v9, v69
	v_cvt_pk_fp8_f32 v9, v11, v13
	v_mul_f32_e32 v3, 0x43800000, v29
	v_mul_f32_e32 v5, 0x43800000, v31
	v_cvt_pk_fp8_f32 v8, v3, v5 op_sel:[0,0,1]
	v_mul_f32_e32 v3, 0x43800000, v87
	v_mul_f32_e32 v5, 0x43800000, v89
	v_cvt_pk_fp8_f32 v9, v3, v5 op_sel:[0,0,1]
	v_mul_f32_e32 v3, 0x43800000, v4
	v_mul_f32_e32 v5, 0x43800000, v10
	v_mov_b32_e32 v4, v69
	ds_read_b32 v13, v84 offset:1020
	v_cvt_pk_fp8_f32 v4, v3, v5
	v_mul_f32_e32 v3, 0x43800000, v12
	v_mul_f32_e32 v11, 0x43800000, v16
	v_mul_f32_e32 v12, 0x43800000, v18
	v_mov_b32_e32 v5, v69
	v_cvt_pk_fp8_f32 v5, v11, v12
	v_mul_f32_e32 v10, 0x43800000, v14
	v_cvt_pk_fp8_f32 v4, v3, v10 op_sel:[0,0,1]
	v_mul_f32_e32 v3, 0x43800000, v20
	s_waitcnt lgkmcnt(0)
	v_mul_f32_e32 v10, 0x43800000, v13
	v_cvt_pk_fp8_f32 v5, v3, v10 op_sel:[0,0,1]
	v_lshl_add_u64 v[10:11], v[6:7], 0, v[74:75]
	v_lshl_add_u64 v[6:7], v[6:7], 0, v[76:77]
	global_store_dwordx2 v[10:11], v[8:9], off
	global_store_dwordx2 v[6:7], v[4:5], off
	s_cbranch_execnz .LBB0_38
	s_branch .LBB0_37

;     __device__ __forceinline__ void operator()(f32x4 (&acc)[2][2][4][2], const Unit& u, int wr, int wc, int fr, int fq) const {
;     ...
;         const h16* gbase = PG + (size_t)(u.pm * 32 + 2 * u.pn) * 65536 + (u.half == 0 ? 0 : 32768) + (wr * 4 + wc) * 512 + (fq * 16 + fr) * 8;
; #pragma unroll
;         for (int ai = 0; ai < 2; ++ai) {
;             h16x8 gt[4][2];
; #pragma unroll
;             for (int m = 0; m < 4; ++m)
; #pragma unroll
;                 for (int bj = 0; bj < 2; ++bj) gt[m][bj] = *(const h16x8*)(gbase + (size_t)bj * 65536 + (ai * 4 + m) * 4096);
;             if (u.half == 0) {
; #pragma unroll
;                 for (int m = 0; m < 4; ++m)
; #pragma unroll
;                     for (int bj = 0; bj < 2; ++bj)
; #pragma unroll
;                         for (int j = 0; j < 4; ++j) { acc[ai][bj][m][0][j] *= (float)gt[m][bj][j]; acc[ai][bj][m][1][j] *= (float)gt[m][bj][4 + j]; }
.LBB0_474:
	s_lshl_b32 s4, s44, 5
	s_lshl_b32 s5, s45, 1
	s_add_i32 s4, s4, s5
	s_ashr_i32 s5, s4, 31
	s_lshl_b64 s[4:5], s[4:5], 17
	s_add_u32 s27, s61, s4
	s_addc_u32 s29, s62, s5
	s_cmp_lg_u32 s80, 0
	s_cselect_b64 s[46:47], -1, 0
	s_cmp_eq_u32 s80, 0
	s_cselect_b64 s[4:5], -1, 0
	s_and_b64 s[4:5], s[4:5], exec
	s_cselect_b32 s48, 0, 0x10000
	s_add_u32 s27, s27, s48
	s_addc_u32 s29, s29, 0
	s_add_u32 s48, s27, s18
	s_addc_u32 s49, s29, s19
	v_lshl_add_u64 v[146:147], s[48:49], 0, v[132:133]
	v_add_co_u32_e32 v142, vcc, s72, v146
	global_load_dwordx4 v[148:151], v132, s[48:49] nt
	s_nop 0
	v_addc_co_u32_e32 v143, vcc, 0, v147, vcc
	global_load_dwordx4 v[152:155], v[142:143], off nt
	v_add_co_u32_e32 v142, vcc, s59, v146
	v_lshl_add_u32 v144, s44, 8, v213
	s_nop 0
	v_addc_co_u32_e32 v143, vcc, 0, v147, vcc
	global_load_dwordx4 v[156:159], v[142:143], off nt
	v_add_co_u32_e32 v142, vcc, 0x22000, v146
	v_ashrrev_i32_e32 v145, 31, v144
	s_nop 0
	v_addc_co_u32_e32 v143, vcc, 0, v147, vcc
	global_load_dwordx4 v[160:163], v[142:143], off nt
	v_add_co_u32_e32 v142, vcc, s60, v146
	s_waitcnt vmcnt(0)
	v_cvt_f32_f16_sdwa v205, v150 dst_sel:DWORD dst_unused:UNUSED_PAD src0_sel:WORD_1
	v_addc_co_u32_e32 v143, vcc, 0, v147, vcc
	global_load_dwordx4 v[164:167], v[142:143], off nt
	v_add_co_u32_e32 v142, vcc, 0x24000, v146
	v_cvt_f32_f16_e32 v208, v148
	s_nop 0
	v_addc_co_u32_e32 v143, vcc, 0, v147, vcc
	global_load_dwordx4 v[218:221], v[142:143], off nt
	v_add_co_u32_e32 v142, vcc, 0x6000, v146
	v_cvt_f32_f16_e32 v204, v150
	s_nop 0
	v_addc_co_u32_e32 v143, vcc, 0, v147, vcc
	global_load_dwordx4 v[222:225], v[142:143], off nt
	v_add_co_u32_e32 v142, vcc, 0x26000, v146
	v_cvt_f32_f16_sdwa v209, v148 dst_sel:DWORD dst_unused:UNUSED_PAD src0_sel:WORD_1
	s_nop 0
	v_addc_co_u32_e32 v143, vcc, 0, v147, vcc
	global_load_dwordx4 v[226:229], v[142:143], off nt
	v_cvt_f32_f16_e32 v210, v149
	v_cvt_f32_f16_e32 v206, v151
	v_cvt_f32_f16_sdwa v211, v149 dst_sel:DWORD dst_unused:UNUSED_PAD src0_sel:WORD_1
	v_cvt_f32_f16_sdwa v207, v151 dst_sel:DWORD dst_unused:UNUSED_PAD src0_sel:WORD_1
	v_cvt_f32_f16_e32 v200, v152
	v_cvt_f32_f16_e32 v196, v154
	v_cvt_f32_f16_sdwa v201, v152 dst_sel:DWORD dst_unused:UNUSED_PAD src0_sel:WORD_1
	v_cvt_f32_f16_sdwa v197, v154 dst_sel:DWORD dst_unused:UNUSED_PAD src0_sel:WORD_1
	v_cvt_f32_f16_e32 v202, v153
	v_cvt_f32_f16_e32 v198, v155
	v_cvt_f32_f16_sdwa v203, v153 dst_sel:DWORD dst_unused:UNUSED_PAD src0_sel:WORD_1
	v_cvt_f32_f16_sdwa v199, v155 dst_sel:DWORD dst_unused:UNUSED_PAD src0_sel:WORD_1
	v_cvt_f32_f16_e32 v192, v156
	v_cvt_f32_f16_e32 v188, v158
	v_cvt_f32_f16_sdwa v193, v156 dst_sel:DWORD dst_unused:UNUSED_PAD src0_sel:WORD_1
	v_cvt_f32_f16_sdwa v189, v158 dst_sel:DWORD dst_unused:UNUSED_PAD src0_sel:WORD_1
	v_cvt_f32_f16_e32 v194, v157
	v_cvt_f32_f16_e32 v190, v159
	v_cvt_f32_f16_sdwa v195, v157 dst_sel:DWORD dst_unused:UNUSED_PAD src0_sel:WORD_1
	v_cvt_f32_f16_sdwa v191, v159 dst_sel:DWORD dst_unused:UNUSED_PAD src0_sel:WORD_1
	v_cvt_f32_f16_e32 v184, v160
	v_cvt_f32_f16_e32 v180, v162
	v_cvt_f32_f16_sdwa v185, v160 dst_sel:DWORD dst_unused:UNUSED_PAD src0_sel:WORD_1
	v_cvt_f32_f16_sdwa v181, v162 dst_sel:DWORD dst_unused:UNUSED_PAD src0_sel:WORD_1
	v_cvt_f32_f16_e32 v186, v161
	v_cvt_f32_f16_e32 v182, v163
	v_cvt_f32_f16_sdwa v187, v161 dst_sel:DWORD dst_unused:UNUSED_PAD src0_sel:WORD_1
	v_cvt_f32_f16_sdwa v183, v163 dst_sel:DWORD dst_unused:UNUSED_PAD src0_sel:WORD_1
	v_lshl_or_b32 v142, s45, 8, v215
	s_mov_b64 s[44:45], -1
	v_ashrrev_i32_e32 v143, 31, v142
	s_mov_b64 vcc, s[4:5]
	s_waitcnt vmcnt(3)
	v_cvt_f32_f16_e32 v176, v164
	v_cvt_f32_f16_e32 v172, v166
	v_cvt_f32_f16_sdwa v177, v164 dst_sel:DWORD dst_unused:UNUSED_PAD src0_sel:WORD_1
	v_cvt_f32_f16_sdwa v173, v166 dst_sel:DWORD dst_unused:UNUSED_PAD src0_sel:WORD_1
	v_cvt_f32_f16_e32 v178, v165
	v_cvt_f32_f16_e32 v174, v167
	v_cvt_f32_f16_sdwa v179, v165 dst_sel:DWORD dst_unused:UNUSED_PAD src0_sel:WORD_1
	v_cvt_f32_f16_sdwa v175, v167 dst_sel:DWORD dst_unused:UNUSED_PAD src0_sel:WORD_1
	s_waitcnt vmcnt(2)
	v_cvt_f32_f16_e32 v168, v218
	v_cvt_f32_f16_e32 v164, v220
	v_cvt_f32_f16_sdwa v169, v218 dst_sel:DWORD dst_unused:UNUSED_PAD src0_sel:WORD_1
	v_cvt_f32_f16_sdwa v165, v220 dst_sel:DWORD dst_unused:UNUSED_PAD src0_sel:WORD_1
	v_cvt_f32_f16_e32 v170, v219
	v_cvt_f32_f16_e32 v166, v221
	v_cvt_f32_f16_sdwa v171, v219 dst_sel:DWORD dst_unused:UNUSED_PAD src0_sel:WORD_1
	v_cvt_f32_f16_sdwa v167, v221 dst_sel:DWORD dst_unused:UNUSED_PAD src0_sel:WORD_1
	s_waitcnt vmcnt(1)
	v_cvt_f32_f16_e32 v160, v222
	v_cvt_f32_f16_e32 v156, v224
	v_cvt_f32_f16_sdwa v161, v222 dst_sel:DWORD dst_unused:UNUSED_PAD src0_sel:WORD_1
	v_cvt_f32_f16_sdwa v157, v224 dst_sel:DWORD dst_unused:UNUSED_PAD src0_sel:WORD_1
	v_cvt_f32_f16_e32 v162, v223
	v_cvt_f32_f16_e32 v158, v225
	v_cvt_f32_f16_sdwa v163, v223 dst_sel:DWORD dst_unused:UNUSED_PAD src0_sel:WORD_1
	v_cvt_f32_f16_sdwa v159, v225 dst_sel:DWORD dst_unused:UNUSED_PAD src0_sel:WORD_1
	s_waitcnt vmcnt(0)
	v_cvt_f32_f16_e32 v152, v226
	v_cvt_f32_f16_e32 v148, v228
	v_cvt_f32_f16_sdwa v153, v226 dst_sel:DWORD dst_unused:UNUSED_PAD src0_sel:WORD_1
	v_cvt_f32_f16_sdwa v149, v228 dst_sel:DWORD dst_unused:UNUSED_PAD src0_sel:WORD_1
	v_cvt_f32_f16_e32 v154, v227
	v_cvt_f32_f16_e32 v150, v229
	v_cvt_f32_f16_sdwa v155, v227 dst_sel:DWORD dst_unused:UNUSED_PAD src0_sel:WORD_1
	v_cvt_f32_f16_sdwa v151, v229 dst_sel:DWORD dst_unused:UNUSED_PAD src0_sel:WORD_1
	s_cbranch_vccnz .LBB0_476
;     __device__ __forceinline__ void operator()(f32x4 (&acc)[2][2][4][2], const Unit& u, int wr, int wc, int fr, int fq) const {
;     ...
;             } else {
; #pragma unroll
;                 for (int m = 0; m < 4; ++m) { const size_t row = (size_t)(row0 + ai * HALF + m * 16);
; #pragma unroll
;                     for (int bj = 0; bj < 2; ++bj) { const int col = col0 + bj * HALF;
;                         float o[8];
; #pragma unroll
;                         for (int j = 0; j < 4; ++j) { o[j] = acc[ai][bj][m][0][j] * (float)gt[m][bj][j]; o[4 + j] = acc[ai][bj][m][1][j] * (float)gt[m][bj][4 + j]; }
;                         u32x4 w; w.x = pkg(o[0], o[1]); w.y = pkg(o[2], o[3]); w.z = pkg(o[4], o[5]); w.w = pkg(o[6], o[7]);
;                         *(u32x4*)(MG + row * D + col) = w; } }
	v_lshlrev_b64 v[222:223], 13, v[144:145]
	v_mul_f32_e32 v220, v120, v204
	v_mul_f32_e32 v221, v121, v205
	v_mul_f32_e32 v219, v126, v210
	v_mul_f32_e32 v224, v122, v206
	v_mul_f32_e32 v225, v127, v211
	v_mul_f32_e32 v218, v125, v209
	v_mul_f32_e32 v226, v123, v207
	v_cvt_pk_bf16_f32 v219, v219, v225
	v_cvt_pk_bf16_f32 v220, v220, v221
	v_cvt_pk_bf16_f32 v221, v224, v226
	v_lshl_add_u64 v[222:223], s[12:13], 0, v[222:223]
	v_lshlrev_b64 v[224:225], 1, v[142:143]
	v_mul_f32_e32 v217, v124, v208
	v_cvt_pk_bf16_f32 v218, v217, v218
	v_lshl_add_u64 v[222:223], v[222:223], 0, v[224:225]
	global_store_dwordx4 v[222:223], v[218:221], off
	v_mul_f32_e32 v217, v92, v200
	v_mul_f32_e32 v226, v90, v198
	v_mul_f32_e32 v218, v93, v201
	v_mul_f32_e32 v220, v88, v196
	v_mul_f32_e32 v221, v89, v197
	v_mul_f32_e32 v219, v94, v202
	v_cvt_pk_bf16_f32 v218, v217, v218
	v_mul_f32_e32 v227, v95, v203
	v_mul_f32_e32 v228, v91, v199
	v_cvt_pk_bf16_f32 v219, v219, v227
	v_cvt_pk_bf16_f32 v220, v220, v221
	v_cvt_pk_bf16_f32 v221, v226, v228
	global_store_dwordx4 v[222:223], v[218:221], off offset:256
	v_mul_f32_e32 v217, v116, v192
	v_mul_f32_e32 v226, v114, v190
	v_or_b32_e32 v218, 16, v144
	v_ashrrev_i32_e32 v219, 31, v218
	v_lshlrev_b64 v[222:223], 13, v[218:219]
	v_mul_f32_e32 v218, v117, v193
	v_lshl_add_u64 v[222:223], s[12:13], 0, v[222:223]
	v_mul_f32_e32 v220, v112, v188
	v_mul_f32_e32 v221, v113, v189
	v_mul_f32_e32 v219, v118, v194
	v_cvt_pk_bf16_f32 v218, v217, v218
	v_lshl_add_u64 v[222:223], v[222:223], 0, v[224:225]
	v_mul_f32_e32 v227, v119, v195
	v_mul_f32_e32 v228, v115, v191
	v_cvt_pk_bf16_f32 v219, v219, v227
	v_cvt_pk_bf16_f32 v220, v220, v221
	v_cvt_pk_bf16_f32 v221, v226, v228
	global_store_dwordx4 v[222:223], v[218:221], off
	v_mul_f32_e32 v217, v84, v184
	v_mul_f32_e32 v226, v82, v182
	v_mul_f32_e32 v218, v85, v185
	v_mul_f32_e32 v220, v80, v180
	v_mul_f32_e32 v221, v81, v181
	v_mul_f32_e32 v219, v86, v186
	v_cvt_pk_bf16_f32 v218, v217, v218
	v_mul_f32_e32 v227, v87, v187
	v_mul_f32_e32 v228, v83, v183
	v_cvt_pk_bf16_f32 v219, v219, v227
	v_cvt_pk_bf16_f32 v220, v220, v221
	v_cvt_pk_bf16_f32 v221, v226, v228
	global_store_dwordx4 v[222:223], v[218:221], off offset:256
	v_mul_f32_e32 v217, v108, v176
	v_mul_f32_e32 v226, v106, v174
	v_or_b32_e32 v218, 32, v144
	v_ashrrev_i32_e32 v219, 31, v218
	v_lshlrev_b64 v[222:223], 13, v[218:219]
	v_mul_f32_e32 v218, v109, v177
	v_lshl_add_u64 v[222:223], s[12:13], 0, v[222:223]
	v_mul_f32_e32 v220, v104, v172
	v_mul_f32_e32 v221, v105, v173
	v_mul_f32_e32 v219, v110, v178
	v_cvt_pk_bf16_f32 v218, v217, v218
	v_lshl_add_u64 v[222:223], v[222:223], 0, v[224:225]
	v_mul_f32_e32 v227, v111, v179
	v_mul_f32_e32 v228, v107, v175
	v_cvt_pk_bf16_f32 v219, v219, v227
	v_cvt_pk_bf16_f32 v220, v220, v221
	v_cvt_pk_bf16_f32 v221, v226, v228
	global_store_dwordx4 v[222:223], v[218:221], off
	v_mul_f32_e32 v217, v76, v168
	v_mul_f32_e32 v226, v74, v166
	v_mul_f32_e32 v218, v77, v169
	v_mul_f32_e32 v220, v72, v164
	v_mul_f32_e32 v221, v73, v165
	v_mul_f32_e32 v219, v78, v170
	v_cvt_pk_bf16_f32 v218, v217, v218
	v_mul_f32_e32 v227, v79, v171
	v_mul_f32_e32 v228, v75, v167
	v_cvt_pk_bf16_f32 v219, v219, v227
	v_cvt_pk_bf16_f32 v220, v220, v221
	v_cvt_pk_bf16_f32 v221, v226, v228
	global_store_dwordx4 v[222:223], v[218:221], off offset:256
	v_mul_f32_e32 v217, v100, v160
	v_mul_f32_e32 v226, v98, v158
	v_or_b32_e32 v218, 48, v144
	v_ashrrev_i32_e32 v219, 31, v218
	v_lshlrev_b64 v[222:223], 13, v[218:219]
	v_mul_f32_e32 v220, v96, v156
	v_mul_f32_e32 v218, v101, v161
	v_mul_f32_e32 v221, v97, v157
	v_mul_f32_e32 v219, v102, v162
	v_lshl_add_u64 v[222:223], s[12:13], 0, v[222:223]
	v_mul_f32_e32 v227, v103, v163
	v_mul_f32_e32 v228, v99, v159
	v_cvt_pk_bf16_f32 v218, v217, v218
	v_cvt_pk_bf16_f32 v219, v219, v227
	v_cvt_pk_bf16_f32 v220, v220, v221
	v_cvt_pk_bf16_f32 v221, v226, v228
	v_lshl_add_u64 v[222:223], v[222:223], 0, v[224:225]
	global_store_dwordx4 v[222:223], v[218:221], off
	s_mov_b64 s[44:45], 0
	v_mul_f32_e32 v217, v68, v152
	v_mul_f32_e32 v220, v64, v148
	v_mul_f32_e32 v218, v69, v153
	v_mul_f32_e32 v221, v65, v149
	v_mul_f32_e32 v219, v70, v154
	v_mul_f32_e32 v224, v66, v150
	v_mul_f32_e32 v225, v71, v155
	v_mul_f32_e32 v226, v67, v151
	v_cvt_pk_bf16_f32 v218, v217, v218
	v_cvt_pk_bf16_f32 v219, v219, v225
	v_cvt_pk_bf16_f32 v220, v220, v221
	v_cvt_pk_bf16_f32 v221, v224, v226
	global_store_dwordx4 v[222:223], v[218:221], off offset:256

;     __device__ __forceinline__ void operator()(f32x4 (&acc)[2][2][4][2], const Unit& u, int wr, int wc, int fr, int fq) const {
;     ...
;         for (int ai = 0; ai < 2; ++ai) {
;             h16x8 gt[4][2];
; #pragma unroll
;             for (int m = 0; m < 4; ++m)
; #pragma unroll
;                 for (int bj = 0; bj < 2; ++bj) gt[m][bj] = *(const h16x8*)(gbase + (size_t)bj * 65536 + (ai * 4 + m) * 4096);
;             if (u.half == 0) {
; #pragma unroll
;                 for (int m = 0; m < 4; ++m)
; #pragma unroll
;                     for (int bj = 0; bj < 2; ++bj)
; #pragma unroll
;                         for (int j = 0; j < 4; ++j) { acc[ai][bj][m][0][j] *= (float)gt[m][bj][j]; acc[ai][bj][m][1][j] *= (float)gt[m][bj][4 + j]; }
.LBB0_478:
	v_add_co_u32_e32 v148, vcc, s63, v146
	v_cndmask_b32_e64 v210, 0, 1, s[46:47]
	s_nop 0
	v_addc_co_u32_e32 v149, vcc, 0, v147, vcc
	v_add_co_u32_e32 v152, vcc, s73, v146
	global_load_dwordx4 v[148:151], v[148:149], off nt
	s_nop 0
	v_addc_co_u32_e32 v153, vcc, 0, v147, vcc
	v_add_co_u32_e32 v156, vcc, s67, v146
	global_load_dwordx4 v[152:155], v[152:153], off nt
	s_nop 0
	v_addc_co_u32_e32 v157, vcc, 0, v147, vcc
	v_add_co_u32_e32 v160, vcc, 0x2a000, v146
	global_load_dwordx4 v[156:159], v[156:157], off nt
	s_nop 0
	v_addc_co_u32_e32 v161, vcc, 0, v147, vcc
	v_add_co_u32_e32 v164, vcc, s71, v146
	global_load_dwordx4 v[160:163], v[160:161], off nt
	s_nop 0
	v_addc_co_u32_e32 v165, vcc, 0, v147, vcc
	v_add_co_u32_e32 v168, vcc, 0x2c000, v146
	global_load_dwordx4 v[164:167], v[164:165], off nt
	s_nop 0
	v_addc_co_u32_e32 v169, vcc, 0, v147, vcc
	global_load_dwordx4 v[218:221], v[168:169], off nt
	v_add_co_u32_e32 v168, vcc, 0xe000, v146
	v_cmp_ne_u32_e64 s[4:5], 1, v210
	s_nop 0
	v_addc_co_u32_e32 v169, vcc, 0, v147, vcc
	v_add_co_u32_e32 v146, vcc, 0x2e000, v146
	global_load_dwordx4 v[222:225], v[168:169], off nt
	s_nop 0
	v_addc_co_u32_e32 v147, vcc, 0, v147, vcc
	global_load_dwordx4 v[226:229], v[146:147], off nt
	s_andn2_b64 vcc, exec, s[46:47]
	s_mov_b64 s[44:45], -1
	s_waitcnt vmcnt(7)
	v_cvt_f32_f16_e32 v206, v149
	v_cvt_f32_f16_e32 v208, v148
	v_cvt_f32_f16_e32 v202, v150
	v_cvt_f32_f16_sdwa v209, v148 dst_sel:DWORD dst_unused:UNUSED_PAD src0_sel:WORD_1
	v_cvt_f32_f16_sdwa v203, v150 dst_sel:DWORD dst_unused:UNUSED_PAD src0_sel:WORD_1
	v_cvt_f32_f16_e32 v204, v151
	v_cvt_f32_f16_sdwa v207, v149 dst_sel:DWORD dst_unused:UNUSED_PAD src0_sel:WORD_1
	v_cvt_f32_f16_sdwa v205, v151 dst_sel:DWORD dst_unused:UNUSED_PAD src0_sel:WORD_1
	s_waitcnt vmcnt(6)
	v_cvt_f32_f16_e32 v198, v152
	v_cvt_f32_f16_e32 v194, v154
	v_cvt_f32_f16_sdwa v199, v152 dst_sel:DWORD dst_unused:UNUSED_PAD src0_sel:WORD_1
	v_cvt_f32_f16_sdwa v195, v154 dst_sel:DWORD dst_unused:UNUSED_PAD src0_sel:WORD_1
	v_cvt_f32_f16_e32 v200, v153
	v_cvt_f32_f16_e32 v196, v155
	v_cvt_f32_f16_sdwa v201, v153 dst_sel:DWORD dst_unused:UNUSED_PAD src0_sel:WORD_1
	v_cvt_f32_f16_sdwa v197, v155 dst_sel:DWORD dst_unused:UNUSED_PAD src0_sel:WORD_1
	s_waitcnt vmcnt(5)
	v_cvt_f32_f16_e32 v190, v156
	v_cvt_f32_f16_e32 v186, v158
	v_cvt_f32_f16_sdwa v191, v156 dst_sel:DWORD dst_unused:UNUSED_PAD src0_sel:WORD_1
	v_cvt_f32_f16_sdwa v187, v158 dst_sel:DWORD dst_unused:UNUSED_PAD src0_sel:WORD_1
	v_cvt_f32_f16_e32 v192, v157
	v_cvt_f32_f16_e32 v188, v159
	v_cvt_f32_f16_sdwa v193, v157 dst_sel:DWORD dst_unused:UNUSED_PAD src0_sel:WORD_1
	v_cvt_f32_f16_sdwa v189, v159 dst_sel:DWORD dst_unused:UNUSED_PAD src0_sel:WORD_1
	s_waitcnt vmcnt(4)
	v_cvt_f32_f16_e32 v182, v160
	v_cvt_f32_f16_e32 v178, v162
	v_cvt_f32_f16_sdwa v183, v160 dst_sel:DWORD dst_unused:UNUSED_PAD src0_sel:WORD_1
	v_cvt_f32_f16_sdwa v179, v162 dst_sel:DWORD dst_unused:UNUSED_PAD src0_sel:WORD_1
	v_cvt_f32_f16_e32 v184, v161
	v_cvt_f32_f16_e32 v180, v163
	v_cvt_f32_f16_sdwa v185, v161 dst_sel:DWORD dst_unused:UNUSED_PAD src0_sel:WORD_1
	v_cvt_f32_f16_sdwa v181, v163 dst_sel:DWORD dst_unused:UNUSED_PAD src0_sel:WORD_1
	s_waitcnt vmcnt(3)
	v_cvt_f32_f16_e32 v174, v164
	v_cvt_f32_f16_e32 v170, v166
	v_cvt_f32_f16_sdwa v175, v164 dst_sel:DWORD dst_unused:UNUSED_PAD src0_sel:WORD_1
	v_cvt_f32_f16_sdwa v171, v166 dst_sel:DWORD dst_unused:UNUSED_PAD src0_sel:WORD_1
	v_cvt_f32_f16_e32 v176, v165
	v_cvt_f32_f16_e32 v172, v167
	v_cvt_f32_f16_sdwa v177, v165 dst_sel:DWORD dst_unused:UNUSED_PAD src0_sel:WORD_1
	v_cvt_f32_f16_sdwa v173, v167 dst_sel:DWORD dst_unused:UNUSED_PAD src0_sel:WORD_1
	s_waitcnt vmcnt(2)
	v_cvt_f32_f16_e32 v166, v218
	v_cvt_f32_f16_e32 v162, v220
	v_cvt_f32_f16_sdwa v167, v218 dst_sel:DWORD dst_unused:UNUSED_PAD src0_sel:WORD_1
	v_cvt_f32_f16_sdwa v163, v220 dst_sel:DWORD dst_unused:UNUSED_PAD src0_sel:WORD_1
	v_cvt_f32_f16_e32 v168, v219
	v_cvt_f32_f16_e32 v164, v221
	v_cvt_f32_f16_sdwa v169, v219 dst_sel:DWORD dst_unused:UNUSED_PAD src0_sel:WORD_1
	v_cvt_f32_f16_sdwa v165, v221 dst_sel:DWORD dst_unused:UNUSED_PAD src0_sel:WORD_1
	s_waitcnt vmcnt(1)
	v_cvt_f32_f16_e32 v158, v222
	v_cvt_f32_f16_e32 v154, v224
	v_cvt_f32_f16_sdwa v159, v222 dst_sel:DWORD dst_unused:UNUSED_PAD src0_sel:WORD_1
	v_cvt_f32_f16_sdwa v155, v224 dst_sel:DWORD dst_unused:UNUSED_PAD src0_sel:WORD_1
	v_cvt_f32_f16_e32 v160, v223
	v_cvt_f32_f16_e32 v156, v225
	v_cvt_f32_f16_sdwa v161, v223 dst_sel:DWORD dst_unused:UNUSED_PAD src0_sel:WORD_1
	v_cvt_f32_f16_sdwa v157, v225 dst_sel:DWORD dst_unused:UNUSED_PAD src0_sel:WORD_1
	s_waitcnt vmcnt(0)
	v_cvt_f32_f16_e32 v150, v226
	v_cvt_f32_f16_e32 v146, v228
	v_cvt_f32_f16_sdwa v151, v226 dst_sel:DWORD dst_unused:UNUSED_PAD src0_sel:WORD_1
	v_cvt_f32_f16_sdwa v147, v228 dst_sel:DWORD dst_unused:UNUSED_PAD src0_sel:WORD_1
	v_cvt_f32_f16_e32 v152, v227
	v_cvt_f32_f16_e32 v148, v229
	v_cvt_f32_f16_sdwa v153, v227 dst_sel:DWORD dst_unused:UNUSED_PAD src0_sel:WORD_1
	v_cvt_f32_f16_sdwa v149, v229 dst_sel:DWORD dst_unused:UNUSED_PAD src0_sel:WORD_1
	s_cbranch_vccnz .LBB0_480
;     __device__ __forceinline__ void operator()(f32x4 (&acc)[2][2][4][2], const Unit& u, int wr, int wc, int fr, int fq) const {
;     ...
;                 for (int m = 0; m < 4; ++m) { const size_t row = (size_t)(row0 + ai * HALF + m * 16);
; #pragma unroll
;                     for (int bj = 0; bj < 2; ++bj) { const int col = col0 + bj * HALF;
;                         float o[8];
; #pragma unroll
;                         for (int j = 0; j < 4; ++j) { o[j] = acc[ai][bj][m][0][j] * (float)gt[m][bj][j]; o[4 + j] = acc[ai][bj][m][1][j] * (float)gt[m][bj][4 + j]; }
;                         u32x4 w; w.x = pkg(o[0], o[1]); w.y = pkg(o[2], o[3]); w.z = pkg(o[4], o[5]); w.w = pkg(o[6], o[7]);
;                         *(u32x4*)(MG + row * D + col) = w; } }
	v_lshlrev_b64 v[144:145], 13, v[144:145]
	v_mul_f32_e32 v210, v60, v208
	v_mul_f32_e32 v211, v56, v202
	v_mul_f32_e32 v220, v57, v203
	v_lshl_add_u64 v[144:145], s[12:13], 0, v[144:145]
	v_mul_f32_e32 v217, v61, v209
	v_cvt_pk_bf16_f32 v218, v210, v217
	v_cvt_pk_bf16_f32 v220, v211, v220
	v_lshl_add_u64 v[210:211], v[142:143], 1, v[144:145]
	v_add_co_u32_e32 v142, vcc, s74, v210
	v_mul_f32_e32 v219, v62, v206
	v_mul_f32_e32 v221, v58, v204
	v_mul_f32_e32 v222, v63, v207
	v_mul_f32_e32 v223, v59, v205
	v_addc_co_u32_e32 v143, vcc, 0, v211, vcc
	v_mul_f32_e32 v144, v24, v194
	v_mul_f32_e32 v145, v25, v195
	v_cvt_pk_bf16_f32 v219, v219, v222
	v_cvt_pk_bf16_f32 v221, v221, v223
	v_lshl_add_u64 v[222:223], v[210:211], 0, s[8:9]
	global_store_dwordx4 v[142:143], v[218:221], off
	v_mul_f32_e32 v142, v28, v198
	v_mul_f32_e32 v143, v29, v199
	v_mul_f32_e32 v218, v26, v196
	v_mul_f32_e32 v220, v27, v197
	v_cvt_pk_bf16_f32 v144, v144, v145
	v_cvt_pk_bf16_f32 v145, v218, v220
	v_mul_f32_e32 v217, v30, v200
	v_mul_f32_e32 v219, v31, v201
	v_cvt_pk_bf16_f32 v142, v142, v143
	v_cvt_pk_bf16_f32 v143, v217, v219
	global_store_dwordx4 v[222:223], v[142:145], off offset:256
	v_mul_f32_e32 v220, v51, v189
	v_mul_f32_e32 v218, v50, v188
	v_mul_f32_e32 v144, v48, v186
	v_mul_f32_e32 v145, v49, v187
	v_cvt_pk_bf16_f32 v144, v144, v145
	v_cvt_pk_bf16_f32 v145, v218, v220
	v_add_co_u32_e32 v220, vcc, s75, v210
	v_mul_f32_e32 v142, v52, v190
	v_mul_f32_e32 v143, v53, v191
	v_addc_co_u32_e32 v221, vcc, 0, v211, vcc
	v_mul_f32_e32 v217, v54, v192
	v_mul_f32_e32 v219, v55, v193
	v_cvt_pk_bf16_f32 v142, v142, v143
	v_cvt_pk_bf16_f32 v143, v217, v219
	global_store_dwordx4 v[220:221], v[142:145], off
	v_lshl_add_u64 v[218:219], v[210:211], 0, s[20:21]
	v_mul_f32_e32 v220, v18, v180
	v_mul_f32_e32 v144, v16, v178
	v_mul_f32_e32 v145, v17, v179
	v_mul_f32_e32 v142, v20, v182
	v_mul_f32_e32 v143, v21, v183
	v_mul_f32_e32 v222, v19, v181
	v_cvt_pk_bf16_f32 v144, v144, v145
	v_cvt_pk_bf16_f32 v145, v220, v222
	v_mul_f32_e32 v217, v22, v184
	v_mul_f32_e32 v221, v23, v185
	v_cvt_pk_bf16_f32 v142, v142, v143
	v_cvt_pk_bf16_f32 v143, v217, v221
	global_store_dwordx4 v[218:219], v[142:145], off offset:256
	v_mul_f32_e32 v220, v43, v173
	v_mul_f32_e32 v218, v42, v172
	v_mul_f32_e32 v144, v40, v170
	v_mul_f32_e32 v145, v41, v171
	v_mul_f32_e32 v142, v44, v174
	v_mul_f32_e32 v143, v45, v175
	v_cvt_pk_bf16_f32 v144, v144, v145
	v_cvt_pk_bf16_f32 v145, v218, v220
	v_add_co_u32_e32 v220, vcc, s76, v210
	v_mul_f32_e32 v217, v46, v176
	v_mul_f32_e32 v219, v47, v177
	v_cvt_pk_bf16_f32 v142, v142, v143
	v_cvt_pk_bf16_f32 v143, v217, v219
	v_addc_co_u32_e32 v221, vcc, 0, v211, vcc
	global_store_dwordx4 v[220:221], v[142:145], off
	v_lshl_add_u64 v[218:219], v[210:211], 0, s[22:23]
	v_mul_f32_e32 v217, v14, v168
	v_mul_f32_e32 v142, v12, v166
	v_mul_f32_e32 v144, v8, v162
	v_mul_f32_e32 v143, v13, v167
	v_mul_f32_e32 v145, v9, v163
	v_mul_f32_e32 v220, v10, v164
	v_mul_f32_e32 v221, v15, v169
	v_mul_f32_e32 v222, v11, v165
	v_cvt_pk_bf16_f32 v142, v142, v143
	v_cvt_pk_bf16_f32 v143, v217, v221
	v_cvt_pk_bf16_f32 v144, v144, v145
	v_cvt_pk_bf16_f32 v145, v220, v222
	global_store_dwordx4 v[218:219], v[142:145], off offset:256
	v_mul_f32_e32 v218, v34, v156
	v_mul_f32_e32 v219, v39, v161
	v_mul_f32_e32 v142, v36, v158
	v_mul_f32_e32 v144, v32, v154
	v_mul_f32_e32 v143, v37, v159
	v_mul_f32_e32 v145, v33, v155
	v_mul_f32_e32 v217, v38, v160
	v_mul_f32_e32 v220, v35, v157
	v_cvt_pk_bf16_f32 v142, v142, v143
	v_cvt_pk_bf16_f32 v143, v217, v219
	v_cvt_pk_bf16_f32 v144, v144, v145
	v_cvt_pk_bf16_f32 v145, v218, v220
	v_lshl_add_u64 v[218:219], v[210:211], 0, s[24:25]
	v_add_co_u32_e32 v210, vcc, s77, v210
	s_mov_b64 s[44:45], 0
	s_nop 0
	v_addc_co_u32_e32 v211, vcc, 0, v211, vcc
	global_store_dwordx4 v[210:211], v[142:145], off
	v_mul_f32_e32 v210, v6, v152
	v_mul_f32_e32 v211, v2, v148
	v_mul_f32_e32 v142, v4, v150
	v_mul_f32_e32 v144, v0, v146
	v_mul_f32_e32 v143, v5, v151
	v_mul_f32_e32 v145, v1, v147
	v_mul_f32_e32 v217, v7, v153
	v_mul_f32_e32 v220, v3, v149
	v_cvt_pk_bf16_f32 v142, v142, v143
	v_cvt_pk_bf16_f32 v143, v210, v217
	v_cvt_pk_bf16_f32 v144, v144, v145
	v_cvt_pk_bf16_f32 v145, v211, v220
	global_store_dwordx4 v[218:219], v[142:145], off offset:256

;     __device__ __forceinline__ void operator()(const f32x4 (&acc)[2][2][4][2], const Unit& u, int wr, int wc, int fr, int fq) const {
;         const int row0 = u.pm * BM + wr * 64 + fr, col0 = u.pn * BM + wc * 32 + 8 * fq;
; #pragma unroll
;         for (int ai = 0; ai < 2; ++ai) {
;             f32x4 xv[4][2][2];
; #pragma unroll
;             for (int m = 0; m < 4; ++m)
; #pragma unroll
;                 for (int bj = 0; bj < 2; ++bj) { const float* xp = x + (size_t)(row0 + ai * HALF + m * 16) * D + col0 + bj * HALF; xv[m][bj][0] = *(const f32x4*)xp; xv[m][bj][1] = *(const f32x4*)(xp + 4); }
; #pragma unroll
;             for (int m = 0; m < 4; ++m) { const size_t row = (size_t)(row0 + ai * HALF + m * 16); float s = 0.f;
; #pragma unroll
;                 for (int bj = 0; bj < 2; ++bj) { const size_t o = row * D + col0 + bj * HALF;
;                     const f32x4 h0 = xv[m][bj][0] + acc[ai][bj][m][0], h1 = xv[m][bj][1] + acc[ai][bj][m][1];
;                     s += (h0[0] * h0[0] + h0[1] * h0[1]) + (h0[2] * h0[2] + h0[3] * h0[3]) + (h1[0] * h1[0] + h1[1] * h1[1]) + (h1[2] * h1[2] + h1[3] * h1[3]);
;                     u32x4 w; w.x = pkh(h0[0], h0[1]); w.y = pkh(h0[2], h0[3]); w.z = pkh(h1[0], h1[1]); w.w = pkh(h1[2], h1[3]);
;                     *(u32x4*)(HB + o) = w; }
;                 s += __shfl_xor(s, 16); s += __shfl_xor(s, 32);
;                 if (fq == 0) (void)__hip_atomic_fetch_add(ssq + row, s, __ATOMIC_RELAXED, __HIP_MEMORY_SCOPE_AGENT); }
.LBB0_563:
	v_lshl_add_u32 v190, s16, 8, v200
	v_lshl_or_b32 v188, s40, 8, v202
	v_ashrrev_i32_e32 v189, 31, v188
	v_ashrrev_i32_e32 v191, 31, v190
	v_lshl_add_u64 v[192:193], v[188:189], 2, s[12:13]
	v_lshlrev_b64 v[128:129], 14, v[190:191]
	v_lshl_add_u64 v[128:129], v[192:193], 0, v[128:129]
	global_load_dwordx4 v[210:213], v[128:129], off nt
	global_load_dwordx4 v[214:217], v[128:129], off offset:16 nt
	global_load_dwordx4 v[218:221], v[128:129], off offset:512 nt
	global_load_dwordx4 v[222:225], v[128:129], off offset:528 nt
	v_or_b32_e32 v198, 16, v190
	v_or_b32_e32 v196, 32, v190
	v_or_b32_e32 v194, 48, v190
	v_ashrrev_i32_e32 v199, 31, v198
	v_ashrrev_i32_e32 v197, 31, v196
	v_ashrrev_i32_e32 v195, 31, v194
	v_lshlrev_b64 v[128:129], 14, v[198:199]
	v_lshlrev_b64 v[130:131], 14, v[196:197]
	v_lshlrev_b64 v[132:133], 14, v[194:195]
	v_lshl_add_u64 v[128:129], v[192:193], 0, v[128:129]
	v_lshl_add_u64 v[130:131], v[192:193], 0, v[130:131]
	v_lshl_add_u64 v[132:133], v[192:193], 0, v[132:133]
	global_load_dwordx4 v[168:171], v[128:129], off offset:16 nt
	global_load_dwordx4 v[172:175], v[128:129], off nt
	global_load_dwordx4 v[160:163], v[128:129], off offset:528 nt
	global_load_dwordx4 v[164:167], v[128:129], off offset:512 nt
	global_load_dwordx4 v[152:155], v[130:131], off offset:16 nt
	global_load_dwordx4 v[156:159], v[130:131], off nt
	global_load_dwordx4 v[144:147], v[130:131], off offset:528 nt
	global_load_dwordx4 v[148:151], v[130:131], off offset:512 nt
	global_load_dwordx4 v[136:139], v[132:133], off offset:16 nt
	global_load_dwordx4 v[140:143], v[132:133], off nt
	s_nop 0
	global_load_dwordx4 v[128:131], v[132:133], off offset:528 nt
	s_nop 0
	global_load_dwordx4 v[132:135], v[132:133], off offset:512 nt
	v_and_b32_e32 v208, 64, v206
	v_xor_b32_e32 v207, 16, v206
	v_add_u32_e32 v208, 64, v208
	v_xor_b32_e32 v209, 32, v206
	v_cmp_lt_i32_e32 vcc, v207, v208
	v_lshlrev_b64 v[226:227], 13, v[190:191]
	v_lshl_add_u64 v[226:227], s[14:15], 0, v[226:227]
	v_cndmask_b32_e32 v207, v206, v207, vcc
	v_cmp_lt_i32_e32 vcc, v209, v208
	v_lshlrev_b32_e32 v208, 2, v207
	s_waitcnt vmcnt(0)
	v_pk_add_f32 v[126:127], v[126:127], v[212:213]
	v_cndmask_b32_e32 v209, v206, v209, vcc
	v_pk_add_f32 v[124:125], v[124:125], v[210:211]
	v_pk_add_f32 v[122:123], v[122:123], v[216:217]
	v_pk_add_f32 v[120:121], v[120:121], v[214:215]
	v_pk_add_f32 v[118:119], v[118:119], v[220:221]
	v_pk_add_f32 v[116:117], v[116:117], v[218:219]
	v_lshlrev_b32_e32 v207, 2, v209
	v_pk_add_f32 v[210:211], v[114:115], v[224:225]
	v_pk_add_f32 v[212:213], v[112:113], v[222:223]
	v_mul_f32_e32 v209, v125, v125
	v_mul_f32_e32 v214, v127, v127
	v_mul_f32_e32 v215, v121, v121
	v_mul_f32_e32 v216, v123, v123
	v_cvt_pk_f16_f32 v114, v120, v121
	v_cvt_pk_f16_f32 v115, v122, v123
	v_mul_f32_e32 v121, v117, v117
	v_mul_f32_e32 v123, v119, v119
	v_cvt_pk_f16_f32 v112, v124, v125
	v_mul_f32_e32 v125, v213, v213
	v_fmac_f32_e32 v209, v124, v124
	v_fmac_f32_e32 v214, v126, v126
	v_fmac_f32_e32 v121, v116, v116
	v_fmac_f32_e32 v123, v118, v118
	v_cvt_pk_f16_f32 v113, v126, v127
	v_mul_f32_e32 v127, v211, v211
	v_fmac_f32_e32 v215, v120, v120
	v_fmac_f32_e32 v125, v212, v212
	v_add_f32_e32 v120, v209, v214
	v_add_f32_e32 v121, v121, v123
	v_fmac_f32_e32 v216, v122, v122
	v_fmac_f32_e32 v127, v210, v210
	v_add_f32_e32 v120, v120, v215
	v_add_f32_e32 v121, v121, v125
	v_add_f32_e32 v120, v216, v120
	v_add_f32_e32 v121, v127, v121
	v_add_f32_e32 v122, v120, v121
	ds_bpermute_b32 v123, v208, v122
	v_lshl_add_u64 v[120:121], v[188:189], 1, v[226:227]
	global_store_dwordx4 v[120:121], v[112:115], off
	v_cvt_pk_f16_f32 v116, v116, v117
	v_cvt_pk_f16_f32 v117, v118, v119
	s_waitcnt lgkmcnt(0)
	v_add_f32_e32 v114, v122, v123
	ds_bpermute_b32 v115, v207, v114
	v_cvt_pk_f16_f32 v118, v212, v213
	v_cvt_pk_f16_f32 v119, v210, v211
	v_lshl_add_u64 v[112:113], v[190:191], 2, s[10:11]
	global_store_dwordx4 v[120:121], v[116:119], off offset:256
	s_and_saveexec_b64 s[38:39], s[0:1]
	s_cbranch_execz .LBB0_565
	s_waitcnt lgkmcnt(0)
	v_add_f32_e32 v114, v114, v115
	global_atomic_add_f32 v[112:113], v114, off

;     __device__ __forceinline__ void operator()(const f32x4 (&acc)[2][2][4][2], const Unit& u, int wr, int wc, int fr, int fq) const {
;     ...
;         for (int ai = 0; ai < 2; ++ai) {
;             f32x4 xv[4][2][2];
; #pragma unroll
;             for (int m = 0; m < 4; ++m)
; #pragma unroll
;                 for (int bj = 0; bj < 2; ++bj) { const float* xp = x + (size_t)(row0 + ai * HALF + m * 16) * D + col0 + bj * HALF; xv[m][bj][0] = *(const f32x4*)xp; xv[m][bj][1] = *(const f32x4*)(xp + 4); }
; #pragma unroll
;             for (int m = 0; m < 4; ++m) { const size_t row = (size_t)(row0 + ai * HALF + m * 16); float s = 0.f;
; #pragma unroll
;                 for (int bj = 0; bj < 2; ++bj) { const size_t o = row * D + col0 + bj * HALF;
;                     const f32x4 h0 = xv[m][bj][0] + acc[ai][bj][m][0], h1 = xv[m][bj][1] + acc[ai][bj][m][1];
;                     s += (h0[0] * h0[0] + h0[1] * h0[1]) + (h0[2] * h0[2] + h0[3] * h0[3]) + (h1[0] * h1[0] + h1[1] * h1[1]) + (h1[2] * h1[2] + h1[3] * h1[3]);
;                     u32x4 w; w.x = pkh(h0[0], h0[1]); w.y = pkh(h0[2], h0[3]); w.z = pkh(h1[0], h1[1]); w.w = pkh(h1[2], h1[3]);
;                     *(u32x4*)(HB + o) = w; }
;                 s += __shfl_xor(s, 16); s += __shfl_xor(s, 32);
;                 if (fq == 0) (void)__hip_atomic_fetch_add(ssq + row, s, __ATOMIC_RELAXED, __HIP_MEMORY_SCOPE_AGENT); }
.LBB0_571:
	s_or_b64 exec, exec, s[38:39]
	v_add_u32_e32 v136, 0x80, v190
	v_ashrrev_i32_e32 v137, 31, v136
	s_waitcnt lgkmcnt(0)
	v_lshlrev_b64 v[64:65], 14, v[136:137]
	v_lshl_add_u64 v[64:65], v[192:193], 0, v[64:65]
	global_load_dwordx4 v[120:123], v[64:65], off nt
	global_load_dwordx4 v[124:127], v[64:65], off offset:16 nt
	global_load_dwordx4 v[128:131], v[64:65], off offset:512 nt
	global_load_dwordx4 v[132:135], v[64:65], off offset:528 nt
	v_add_u32_e32 v118, 0x90, v190
	v_add_u32_e32 v116, 0xa0, v190
	v_add_u32_e32 v114, 0xb0, v190
	v_ashrrev_i32_e32 v119, 31, v118
	v_ashrrev_i32_e32 v117, 31, v116
	v_ashrrev_i32_e32 v115, 31, v114
	v_lshlrev_b64 v[64:65], 14, v[118:119]
	v_lshlrev_b64 v[66:67], 14, v[116:117]
	v_lshlrev_b64 v[68:69], 14, v[114:115]
	v_lshl_add_u64 v[64:65], v[192:193], 0, v[64:65]
	v_lshl_add_u64 v[66:67], v[192:193], 0, v[66:67]
	v_lshl_add_u64 v[68:69], v[192:193], 0, v[68:69]
	global_load_dwordx4 v[104:107], v[64:65], off offset:16 nt
	global_load_dwordx4 v[108:111], v[64:65], off nt
	global_load_dwordx4 v[96:99], v[64:65], off offset:528 nt
	global_load_dwordx4 v[100:103], v[64:65], off offset:512 nt
	global_load_dwordx4 v[88:91], v[66:67], off offset:16 nt
	global_load_dwordx4 v[92:95], v[66:67], off nt
	global_load_dwordx4 v[80:83], v[66:67], off offset:528 nt
	global_load_dwordx4 v[84:87], v[66:67], off offset:512 nt
	global_load_dwordx4 v[72:75], v[68:69], off offset:16 nt
	global_load_dwordx4 v[76:79], v[68:69], off nt
	s_nop 0
	global_load_dwordx4 v[64:67], v[68:69], off offset:528 nt
	s_nop 0
	global_load_dwordx4 v[68:71], v[68:69], off offset:512 nt
	v_lshlrev_b64 v[136:137], 13, v[136:137]
	s_waitcnt vmcnt(15)
	v_pk_add_f32 v[62:63], v[62:63], v[122:123]
	v_pk_add_f32 v[60:61], v[60:61], v[120:121]
	s_waitcnt vmcnt(14)
	v_pk_add_f32 v[58:59], v[58:59], v[126:127]
	v_pk_add_f32 v[56:57], v[56:57], v[124:125]
	s_waitcnt vmcnt(13)
	v_pk_add_f32 v[54:55], v[54:55], v[130:131]
	v_pk_add_f32 v[52:53], v[52:53], v[128:129]
	s_waitcnt vmcnt(12)
	v_pk_add_f32 v[120:121], v[50:51], v[134:135]
	v_pk_add_f32 v[122:123], v[48:49], v[132:133]
	v_mul_f32_e32 v124, v61, v61
	v_mul_f32_e32 v125, v63, v63
	v_mul_f32_e32 v126, v57, v57
	v_mul_f32_e32 v127, v59, v59
	v_cvt_pk_f16_f32 v50, v56, v57
	v_cvt_pk_f16_f32 v51, v58, v59
	v_mul_f32_e32 v57, v53, v53
	v_mul_f32_e32 v59, v55, v55
	v_cvt_pk_f16_f32 v48, v60, v61
	v_mul_f32_e32 v61, v123, v123
	v_fmac_f32_e32 v124, v60, v60
	v_fmac_f32_e32 v125, v62, v62
	v_fmac_f32_e32 v57, v52, v52
	v_fmac_f32_e32 v59, v54, v54
	v_cvt_pk_f16_f32 v49, v62, v63
	v_mul_f32_e32 v63, v121, v121
	v_fmac_f32_e32 v126, v56, v56
	v_fmac_f32_e32 v61, v122, v122
	v_add_f32_e32 v56, v124, v125
	v_add_f32_e32 v57, v57, v59
	v_fmac_f32_e32 v127, v58, v58
	v_fmac_f32_e32 v63, v120, v120
	v_add_f32_e32 v56, v56, v126
	v_add_f32_e32 v57, v57, v61
	v_add_f32_e32 v56, v127, v56
	v_add_f32_e32 v57, v63, v57
	v_add_f32_e32 v58, v56, v57
	ds_bpermute_b32 v59, v208, v58
	v_lshl_add_u64 v[56:57], s[14:15], 0, v[136:137]
	v_lshl_add_u64 v[56:57], v[188:189], 1, v[56:57]
	global_store_dwordx4 v[56:57], v[48:51], off
	s_waitcnt lgkmcnt(0)
	s_nop 0
	v_add_f32_e32 v48, v58, v59
	ds_bpermute_b32 v49, v207, v48
	v_cvt_pk_f16_f32 v50, v52, v53
	v_cvt_pk_f16_f32 v51, v54, v55
	v_cvt_pk_f16_f32 v52, v122, v123
	v_cvt_pk_f16_f32 v53, v120, v121
	global_store_dwordx4 v[56:57], v[50:53], off offset:256
	s_and_saveexec_b64 s[38:39], s[0:1]
	s_cbranch_execz .LBB0_573
	s_waitcnt lgkmcnt(0)
	v_add_f32_e32 v48, v48, v49
	global_atomic_add_f32 v[112:113], v48, off offset:512

; __device__ __forceinline__ void final_tile(const Unit& u, const h16* HB, float* ssq, unsigned* cnt, const float* fnw, float* out, int tid) {
;     ...
;     for (int rb = wave; rb < BM; rb += 64) {
;         h16x4 hv[8]; float sq[8];
; #pragma unroll
;         for (int q = 0; q < 8; ++q) { const size_t row = (size_t)u.pm * BM + rb + 8 * q; hv[q] = *(const h16x4*)(HB + row * D + c0); sq[q] = __hip_atomic_load(ssq + row, __ATOMIC_RELAXED, __HIP_MEMORY_SCOPE_AGENT); }
; #pragma unroll
;         for (int q = 0; q < 8; ++q) { const size_t row = (size_t)u.pm * BM + rb + 8 * q; const float rs = rsqrtf(sq[q] * (1.f / D) + EPS);
.LBB0_613:
	v_add_co_u32_e32 v26, vcc, 0xfff90000, v14
	v_add_co_u32_e64 v22, s[6:7], s43, v16
	s_nop 0
	v_addc_co_u32_e32 v27, vcc, -1, v15, vcc
	v_add_co_u32_e32 v36, vcc, 0xfffa0000, v14
	global_load_dwordx2 v[38:39], v[26:27], off
	global_load_dword v41, v[18:19], off offset:-128 sc1
	v_addc_co_u32_e32 v37, vcc, -1, v15, vcc
	v_add_co_u32_e32 v26, vcc, 0xfffb0000, v14
	global_load_dwordx2 v[42:43], v[36:37], off
	global_load_dword v40, v[18:19], off offset:-96 sc1
	v_addc_co_u32_e32 v27, vcc, -1, v15, vcc
	v_add_co_u32_e32 v36, vcc, 0xfffc0000, v14
	global_load_dwordx2 v[48:49], v[26:27], off
	global_load_dword v51, v[18:19], off offset:-64 sc1
	v_addc_co_u32_e32 v37, vcc, -1, v15, vcc
	v_add_co_u32_e32 v26, vcc, 0xfffd0000, v14
	global_load_dwordx2 v[52:53], v[36:37], off
	global_load_dword v50, v[18:19], off offset:-32 sc1
	v_addc_co_u32_e32 v27, vcc, -1, v15, vcc
	v_add_co_u32_e32 v36, vcc, 0xfffe0000, v14
	global_load_dwordx2 v[54:55], v[26:27], off
	global_load_dword v57, v[18:19], off sc1
	v_addc_co_u32_e32 v37, vcc, -1, v15, vcc
	v_add_co_u32_e32 v26, vcc, 0xffff0000, v14
	global_load_dwordx2 v[58:59], v[36:37], off
	global_load_dword v56, v[18:19], off offset:32 sc1
	v_addc_co_u32_e32 v27, vcc, -1, v15, vcc
	global_load_dwordx2 v[36:37], v[26:27], off
	global_load_dword v63, v[18:19], off offset:64 sc1
	global_load_dwordx2 v[64:65], v[14:15], off
	global_load_dword v62, v[18:19], off offset:96 sc1
	v_addc_co_u32_e64 v23, s[6:7], 0, v17, s[6:7]
	v_add_co_u32_e64 v24, s[6:7], s44, v16
	v_mov_b64_e32 v[20:21], s[24:25]
	s_nop 0
	v_addc_co_u32_e64 v25, s[6:7], 0, v17, s[6:7]
	v_add_co_u32_e64 v28, s[6:7], s45, v16
	v_add_u32_e32 v35, 64, v35
	s_nop 0
	v_addc_co_u32_e64 v29, s[6:7], 0, v17, s[6:7]
	v_add_co_u32_e64 v30, s[6:7], s48, v16
	v_add_co_u32_e32 v60, vcc, 0xe0000, v16
	s_nop 0
	v_addc_co_u32_e64 v31, s[6:7], 0, v17, s[6:7]
	v_add_co_u32_e64 v44, s[6:7], s49, v16
	v_addc_co_u32_e32 v61, vcc, 0, v17, vcc
	s_nop 0
	v_addc_co_u32_e64 v45, s[6:7], 0, v17, s[6:7]
	v_add_co_u32_e64 v46, s[6:7], s50, v16
	v_lshl_add_u64 v[14:15], v[14:15], 0, s[26:27]
	s_nop 0
	v_addc_co_u32_e64 v47, s[6:7], 0, v17, s[6:7]
	v_cmp_lt_i32_e64 s[6:7], s51, v35
	s_or_b64 s[40:41], s[6:7], s[40:41]
	v_lshl_add_u64 v[18:19], v[18:19], 0, s[34:35]
	s_waitcnt vmcnt(15)
	v_cvt_f32_f16_e32 v26, v38
	v_cvt_f32_f16_sdwa v27, v38 dst_sel:DWORD dst_unused:UNUSED_PAD src0_sel:WORD_1
	v_cvt_f32_f16_e32 v38, v39
	v_cvt_f32_f16_sdwa v39, v39 dst_sel:DWORD dst_unused:UNUSED_PAD src0_sel:WORD_1
	s_waitcnt vmcnt(13)
	v_cvt_f32_f16_e32 v66, v42
	s_waitcnt vmcnt(12)
	v_pk_fma_f32 v[40:41], v[40:41], s[22:23], v[20:21] op_sel_hi:[1,0,0]
	v_cvt_f32_f16_sdwa v67, v42 dst_sel:DWORD dst_unused:UNUSED_PAD src0_sel:WORD_1
	v_mul_f32_e32 v70, 0x4b800000, v41
	v_mul_f32_e32 v71, 0x4b800000, v40
	v_cmp_gt_f32_e32 vcc, s42, v40
	v_cmp_gt_f32_e64 s[6:7], s42, v41
	v_cvt_f32_f16_e32 v42, v43
	v_cndmask_b32_e32 v71, v40, v71, vcc
	v_cndmask_b32_e64 v70, v41, v70, s[6:7]
	v_rsq_f32_e32 v78, v70
	s_waitcnt vmcnt(8)
	v_pk_fma_f32 v[40:41], v[50:51], s[22:23], v[20:21] op_sel_hi:[1,0,0]
	v_rsq_f32_e32 v79, v71
	v_mul_f32_e32 v72, 0x4b800000, v41
	v_mul_f32_e32 v73, 0x4b800000, v40
	v_cmp_gt_f32_e64 s[8:9], s42, v40
	v_cmp_gt_f32_e64 s[10:11], s42, v41
	v_cvt_f32_f16_sdwa v43, v43 dst_sel:DWORD dst_unused:UNUSED_PAD src0_sel:WORD_1
	v_cndmask_b32_e64 v73, v40, v73, s[8:9]
	v_cndmask_b32_e64 v72, v41, v72, s[10:11]
	v_rsq_f32_e32 v80, v72
	s_waitcnt vmcnt(4)
	v_pk_fma_f32 v[40:41], v[56:57], s[22:23], v[20:21] op_sel_hi:[1,0,0]
	v_rsq_f32_e32 v81, v73
	v_mul_f32_e32 v82, 0x4b800000, v41
	v_mul_f32_e32 v83, 0x4b800000, v40
	v_cmp_gt_f32_e64 s[12:13], s42, v40
	s_waitcnt vmcnt(0)
; __device__ __forceinline__ void final_tile(const Unit& u, const h16* HB, float* ssq, unsigned* cnt, const float* fnw, float* out, int tid) {
;     ...
;     for (int rb = wave; rb < BM; rb += 64) {
;         h16x4 hv[8]; float sq[8];
; #pragma unroll
;         for (int q = 0; q < 8; ++q) { const size_t row = (size_t)u.pm * BM + rb + 8 * q; hv[q] = *(const h16x4*)(HB + row * D + c0); sq[q] = __hip_atomic_load(ssq + row, __ATOMIC_RELAXED, __HIP_MEMORY_SCOPE_AGENT); }
; #pragma unroll
;         for (int q = 0; q < 8; ++q) { const size_t row = (size_t)u.pm * BM + rb + 8 * q; const float rs = rsqrtf(sq[q] * (1.f / D) + EPS);
;             f32x4 o; o[0] = (float)hv[q][0] * rs * w4[0]; o[1] = (float)hv[q][1] * rs * w4[1]; o[2] = (float)hv[q][2] * rs * w4[2]; o[3] = (float)hv[q][3] * rs * w4[3];
;             *(f32x4*)(out + row * D + c0) = o; }
	v_pk_fma_f32 v[20:21], v[62:63], s[22:23], v[20:21] op_sel_hi:[1,0,0]
	v_cmp_gt_f32_e64 s[14:15], s42, v41
	v_cvt_f32_f16_e32 v72, v36
	v_cvt_f32_f16_sdwa v73, v36 dst_sel:DWORD dst_unused:UNUSED_PAD src0_sel:WORD_1
	v_cvt_f32_f16_e32 v74, v37
	v_cvt_f32_f16_sdwa v75, v37 dst_sel:DWORD dst_unused:UNUSED_PAD src0_sel:WORD_1
	v_cndmask_b32_e64 v36, v41, v82, s[14:15]
	v_cndmask_b32_e64 v37, v40, v83, s[12:13]
	v_mul_f32_e32 v40, 0x4b800000, v21
	v_cmp_gt_f32_e64 s[18:19], s42, v21
	v_cvt_f32_f16_e32 v68, v48
	v_cvt_f32_f16_sdwa v69, v48 dst_sel:DWORD dst_unused:UNUSED_PAD src0_sel:WORD_1
	v_cvt_f32_f16_e32 v48, v49
	v_cvt_f32_f16_sdwa v49, v49 dst_sel:DWORD dst_unused:UNUSED_PAD src0_sel:WORD_1
	v_cvt_f32_f16_e32 v50, v52
	v_cvt_f32_f16_sdwa v51, v52 dst_sel:DWORD dst_unused:UNUSED_PAD src0_sel:WORD_1
	v_cvt_f32_f16_e32 v52, v53
	v_cvt_f32_f16_sdwa v53, v53 dst_sel:DWORD dst_unused:UNUSED_PAD src0_sel:WORD_1
	v_cvt_f32_f16_sdwa v63, v64 dst_sel:DWORD dst_unused:UNUSED_PAD src0_sel:WORD_1
	v_cvt_f32_f16_e32 v62, v64
	v_cvt_f32_f16_sdwa v77, v65 dst_sel:DWORD dst_unused:UNUSED_PAD src0_sel:WORD_1
	v_cvt_f32_f16_e32 v76, v65
	v_mul_f32_e32 v41, 0x4b800000, v20
	v_cmp_gt_f32_e64 s[16:17], s42, v20
	v_mul_f32_e32 v64, 0x45800000, v78
	v_mul_f32_e32 v65, 0x45800000, v79
	v_rsq_f32_e32 v82, v36
	v_cndmask_b32_e64 v21, v21, v40, s[18:19]
	v_rsq_f32_e32 v83, v37
	v_cndmask_b32_e64 v37, v20, v41, s[16:17]
	v_cndmask_b32_e64 v20, v78, v64, s[6:7]
	v_cndmask_b32_e32 v36, v79, v65, vcc
	v_rsq_f32_e32 v64, v21
	v_cvt_f32_f16_e32 v70, v54
	v_cvt_f32_f16_sdwa v71, v54 dst_sel:DWORD dst_unused:UNUSED_PAD src0_sel:WORD_1
	v_cvt_f32_f16_e32 v54, v55
	v_cvt_f32_f16_sdwa v55, v55 dst_sel:DWORD dst_unused:UNUSED_PAD src0_sel:WORD_1
	v_rsq_f32_e32 v65, v37
	v_pk_mul_f32 v[26:27], v[20:21], v[26:27] op_sel_hi:[0,1]
	v_pk_mul_f32 v[20:21], v[20:21], v[38:39] op_sel_hi:[0,1]
	v_pk_mul_f32 v[40:41], v[36:37], v[66:67] op_sel_hi:[0,1]
	v_pk_mul_f32 v[42:43], v[36:37], v[42:43] op_sel_hi:[0,1]
	v_mul_f32_e32 v66, 0x45800000, v80
	v_mul_f32_e32 v67, 0x45800000, v81
	v_cvt_f32_f16_e32 v56, v58
	v_cvt_f32_f16_sdwa v57, v58 dst_sel:DWORD dst_unused:UNUSED_PAD src0_sel:WORD_1
	v_cvt_f32_f16_e32 v58, v59
	v_cvt_f32_f16_sdwa v59, v59 dst_sel:DWORD dst_unused:UNUSED_PAD src0_sel:WORD_1
	v_pk_mul_f32 v[38:39], v[2:3], v[20:21]
	v_pk_mul_f32 v[36:37], v[0:1], v[26:27]
	v_pk_mul_f32 v[42:43], v[2:3], v[42:43]
	v_pk_mul_f32 v[40:41], v[0:1], v[40:41]
	v_cndmask_b32_e64 v20, v80, v66, s[10:11]
	v_cndmask_b32_e64 v26, v81, v67, s[8:9]
	global_store_dwordx4 v[16:17], v[36:39], off nt
	global_store_dwordx4 v[22:23], v[40:43], off nt
	v_lshl_add_u64 v[16:17], v[16:17], 0, s[28:29]
	v_pk_mul_f32 v[36:37], v[20:21], v[68:69] op_sel_hi:[0,1]
	v_pk_mul_f32 v[20:21], v[20:21], v[48:49] op_sel_hi:[0,1]
	v_pk_mul_f32 v[40:41], v[26:27], v[50:51] op_sel_hi:[0,1]
	v_pk_mul_f32 v[26:27], v[26:27], v[52:53] op_sel_hi:[0,1]
	v_mul_f32_e32 v42, 0x45800000, v82
	v_mul_f32_e32 v43, 0x45800000, v83
	v_pk_mul_f32 v[22:23], v[2:3], v[20:21]
	v_pk_mul_f32 v[20:21], v[0:1], v[36:37]
	v_pk_mul_f32 v[38:39], v[2:3], v[26:27]
	v_pk_mul_f32 v[36:37], v[0:1], v[40:41]
	v_cndmask_b32_e64 v26, v82, v42, s[14:15]
	v_mul_f32_e32 v41, 0x45800000, v64
	v_cndmask_b32_e64 v40, v83, v43, s[12:13]
	v_mul_f32_e32 v42, 0x45800000, v65
	global_store_dwordx4 v[24:25], v[20:23], off nt
	global_store_dwordx4 v[28:29], v[36:39], off nt
	v_cndmask_b32_e64 v28, v64, v41, s[18:19]
	v_pk_mul_f32 v[20:21], v[26:27], v[70:71] op_sel_hi:[0,1]
	v_pk_mul_f32 v[22:23], v[26:27], v[54:55] op_sel_hi:[0,1]
	v_pk_mul_f32 v[24:25], v[40:41], v[56:57] op_sel_hi:[0,1]
	v_pk_mul_f32 v[26:27], v[40:41], v[58:59] op_sel_hi:[0,1]
	v_cndmask_b32_e64 v36, v65, v42, s[16:17]
	v_pk_mul_f32 v[22:23], v[2:3], v[22:23]
	v_pk_mul_f32 v[20:21], v[0:1], v[20:21]
	v_pk_mul_f32 v[38:39], v[28:29], v[72:73] op_sel_hi:[0,1]
	v_pk_mul_f32 v[28:29], v[28:29], v[74:75] op_sel_hi:[0,1]
	v_pk_mul_f32 v[26:27], v[2:3], v[26:27]
	v_pk_mul_f32 v[24:25], v[0:1], v[24:25]
	v_pk_mul_f32 v[40:41], v[36:37], v[62:63] op_sel_hi:[0,1]
	v_pk_mul_f32 v[36:37], v[36:37], v[76:77] op_sel_hi:[0,1]
	global_store_dwordx4 v[30:31], v[20:23], off nt
	global_store_dwordx4 v[44:45], v[24:27], off nt
	s_nop 0
	v_pk_mul_f32 v[22:23], v[2:3], v[28:29]
	v_pk_mul_f32 v[20:21], v[0:1], v[38:39]
	v_pk_mul_f32 v[26:27], v[2:3], v[36:37]
	v_pk_mul_f32 v[24:25], v[0:1], v[40:41]
	global_store_dwordx4 v[46:47], v[20:23], off nt
	global_store_dwordx4 v[60:61], v[24:27], off nt
	s_andn2_b64 exec, exec, s[40:41]
	s_cbranch_execnz .LBB0_613
	s_branch .LBB0_587
